# attention pipelined body with the next tile's LDS staging interleaved into the MFMA stream
# baseline (speedup 1.0000x reference)
; #define LAS __attribute__((address_space(3)))
; __device__ __forceinline__ void attn_phase(LAS unsigned char* ldsb, bf16_t* P, const bf16_t* Kn, const bf16_t* KPE, const bf16_t* VT) {
;     ...
;             ATT_LOAD(0);
;             for (int kt = 0; kt < nt; ++kt) {
;                 __syncthreads();
; #pragma unroll
;                 for (int i = 0; i < 3; ++i) { const int id = tid + 512 * i, row = id / 24, ch = id % 24; *(LAS u32x4*)(sK + row * 200 + ch * 8) = kst[i]; }
; #pragma unroll
;                 for (int i = 0; i < 2; ++i) { const int id = tid + 512 * i, d = id >> 3, ch = id & 7;
;                     *(LAS u32x2*)(sVt + d * 68 + ch * 8) = (u32x2){vst[i].x, vst[i].y}; *(LAS u32x2*)(sVt + d * 68 + ch * 8 + 4) = (u32x2){vst[i].z, vst[i].w}; }
;                 __syncthreads();
;                 if (kt + 1 < nt) ATT_LOAD(kt + 1);
.LBB0_1527:
	s_sub_i32 s12, s78, 63
	s_cmp_gt_i32 s12, s76
	s_cbranch_scc1 .Lattn_stage_skip
	s_cmp_le_i32 s78, s45
	s_cbranch_scc0 .Lattn_stage_slow
	s_cmp_lt_u32 s77, 2
	s_cbranch_scc1 .Lattn_nopre
	s_branch .Lattn_fast_st
.Lattn_stage_skip:
	s_cmp_lt_u32 s77, 2
	s_cbranch_scc1 .LBB0_1526
	s_waitcnt vmcnt(4)
	ds_write_b128 v148, v[112:115]
	s_waitcnt vmcnt(3)
	ds_write_b128 v149, v[116:119]
	s_waitcnt vmcnt(2)
	ds_write_b128 v150, v[120:123]
	s_waitcnt vmcnt(1)
	ds_write2_b64 v151, v[128:129], v[130:131] offset1:1
	s_waitcnt vmcnt(0)
	ds_write2_b64 v152, v[124:125], v[126:127] offset1:1
	s_waitcnt lgkmcnt(0)
	global_load_dwordx4 v[112:115], v136, s[26:27]
	global_load_dwordx4 v[116:119], v140, s[26:27]
	global_load_dwordx4 v[120:123], v144, s[26:27]
	global_load_dwordx4 v[128:131], v132, s[26:27]
	global_load_dwordx4 v[124:127], v134, s[26:27]
	v_add_u32_e32 v132, 0x80, v132
	v_add_u32_e32 v134, 0x80, v134
	v_add_u32_e32 v136, v136, v138
	v_add_u32_e32 v140, v140, v142
	v_add_u32_e32 v144, v144, v146
	s_branch .LBB0_1526

; DI int crow(int reg, int hh) { return (reg & 3) + 8 * (reg >> 2) + 4 * hh; }
; #define ATT_RD(dst, off) asm volatile("ds_read_b128 %0, %1 offset:" #off : "=&v"(dst) : "v"(kaddr) : "memory")
; __device__ __forceinline__ void attn_phase(LAS unsigned char* ldsb, bf16_t* P, const bf16_t* Kn, const bf16_t* KPE, const bf16_t* VT) {
;     ...
;                 const int k0 = kt * 64;
;                 if (k0 <= q0 + w * 32 + 31) {
;                     f32x16 st[2];
; #pragma unroll
;                     for (int kb = 0; kb < 2; ++kb) for (int i = 0; i < 16; ++i) st[kb][i] = 0.f;
;                     {
;                         const unsigned kaddr = (unsigned)(size_t)(sK + r * 200 + hh * 8);
;                         bf16x8 ka0, ka1, kb0, kb1;
;     ...
;                         ATT_RD(ka0, 0);   ATT_RD(ka1, 12800);
;                         ATT_RD(kb0, 32);  ATT_RD(kb1, 12832);  ATT_WT(2, ka0, ka1); ATT_MM(ka0, ka1, 0);
;                         ATT_RD(ka0, 64);  ATT_RD(ka1, 12864);  ATT_WT(2, kb0, kb1); ATT_MM(kb0, kb1, 1);
;                         ATT_RD(kb0, 96);  ATT_RD(kb1, 12896);  ATT_WT(2, ka0, ka1); ATT_MM(ka0, ka1, 2);
;                         ATT_RD(ka0, 128); ATT_RD(ka1, 12928);  ATT_WT(2, kb0, kb1); ATT_MM(kb0, kb1, 3);
;                         ATT_RD(kb0, 160); ATT_RD(kb1, 12960);  ATT_WT(2, ka0, ka1); ATT_MM(ka0, ka1, 4);
;                         ATT_RD(ka0, 192); ATT_RD(ka1, 12992);  ATT_WT(2, kb0, kb1); ATT_MM(kb0, kb1, 5);
;                         ATT_RD(kb0, 224); ATT_RD(kb1, 13024);  ATT_WT(2, ka0, ka1); ATT_MM(ka0, ka1, 6);
;                         ATT_RD(ka0, 256); ATT_RD(ka1, 13056);  ATT_WT(2, kb0, kb1); ATT_MM(kb0, kb1, 7);
;                         ATT_RD(kb0, 288); ATT_RD(kb1, 13088);  ATT_WT(2, ka0, ka1); ATT_MM(ka0, ka1, 8);
;                         ATT_RD(ka0, 320); ATT_RD(ka1, 13120);  ATT_WT(2, kb0, kb1); ATT_MM(kb0, kb1, 9);
;                         ATT_RD(kb0, 352); ATT_RD(kb1, 13152);  ATT_WT(2, ka0, ka1); ATT_MM(ka0, ka1, 10);
;                         ATT_WT(0, kb0, kb1); ATT_MM(kb0, kb1, 11);
;     ...
;                     }
;                     if (k0 + 63 > q0 + w * 32) {
; #pragma unroll
;                         for (int kb = 0; kb < 2; ++kb)
; #pragma unroll
;                             for (int i = 0; i < 16; ++i) { const int key = k0 + kb * 32 + crow(i, hh); if (key > qabs) st[kb][i] = -INFINITY; }
;                     }
.Lattn_nopre:
	ds_read_b128 v[2:5], v241 offset:0
	ds_read_b128 v[6:9], v241 offset:12800
	ds_read_b128 v[10:13], v241 offset:32
	ds_read_b128 v[154:157], v241 offset:12832
	ds_read_b128 v[158:161], v241 offset:64
	ds_read_b128 v[162:165], v241 offset:12864
	ds_read_b128 v[166:169], v241 offset:96
	ds_read_b128 v[170:173], v241 offset:12896
	s_cmp_le_i32 s78, s45
	s_waitcnt lgkmcnt(6)
	v_mfma_f32_32x32x16_bf16 v[96:111], v[2:5], v[220:223], 0
	ds_read_b128 v[2:5], v241 offset:128
	v_mfma_f32_32x32x16_bf16 v[80:95], v[6:9], v[220:223], 0
	ds_read_b128 v[6:9], v241 offset:12928
	s_waitcnt lgkmcnt(6)
	v_mfma_f32_32x32x16_bf16 v[96:111], v[10:13], v[216:219], v[96:111]
	ds_read_b128 v[10:13], v241 offset:160
	v_mfma_f32_32x32x16_bf16 v[80:95], v[154:157], v[216:219], v[80:95]
	ds_read_b128 v[154:157], v241 offset:12960
	s_waitcnt lgkmcnt(6)
	v_mfma_f32_32x32x16_bf16 v[96:111], v[158:161], v[212:215], v[96:111]
	ds_read_b128 v[158:161], v241 offset:192
	v_mfma_f32_32x32x16_bf16 v[80:95], v[162:165], v[212:215], v[80:95]
	ds_read_b128 v[162:165], v241 offset:12992
	s_waitcnt lgkmcnt(6)
	v_mfma_f32_32x32x16_bf16 v[96:111], v[166:169], v[208:211], v[96:111]
	ds_read_b128 v[166:169], v241 offset:224
	v_mfma_f32_32x32x16_bf16 v[80:95], v[170:173], v[208:211], v[80:95]
	ds_read_b128 v[170:173], v241 offset:13024
	s_waitcnt lgkmcnt(6)
	v_mfma_f32_32x32x16_bf16 v[96:111], v[2:5], v[204:207], v[96:111]
	ds_read_b128 v[2:5], v241 offset:256
	v_mfma_f32_32x32x16_bf16 v[80:95], v[6:9], v[204:207], v[80:95]
	ds_read_b128 v[6:9], v241 offset:13056
	s_waitcnt lgkmcnt(6)
	v_mfma_f32_32x32x16_bf16 v[96:111], v[10:13], v[200:203], v[96:111]
	ds_read_b128 v[10:13], v241 offset:288
	v_mfma_f32_32x32x16_bf16 v[80:95], v[154:157], v[200:203], v[80:95]
	ds_read_b128 v[154:157], v241 offset:13088
	s_waitcnt lgkmcnt(6)
	v_mfma_f32_32x32x16_bf16 v[96:111], v[158:161], v[196:199], v[96:111]
	ds_read_b128 v[158:161], v241 offset:320
	v_mfma_f32_32x32x16_bf16 v[80:95], v[162:165], v[196:199], v[80:95]
	ds_read_b128 v[162:165], v241 offset:13120
	s_waitcnt lgkmcnt(6)
	v_mfma_f32_32x32x16_bf16 v[96:111], v[166:169], v[192:195], v[96:111]
	ds_read_b128 v[166:169], v241 offset:352
	v_mfma_f32_32x32x16_bf16 v[80:95], v[170:173], v[192:195], v[80:95]
	ds_read_b128 v[170:173], v241 offset:13152
	s_waitcnt lgkmcnt(6)
	v_mfma_f32_32x32x16_bf16 v[96:111], v[2:5], v[188:191], v[96:111]
	v_mfma_f32_32x32x16_bf16 v[80:95], v[6:9], v[188:191], v[80:95]
	s_waitcnt lgkmcnt(4)
	v_mfma_f32_32x32x16_bf16 v[96:111], v[10:13], v[184:187], v[96:111]
	v_mfma_f32_32x32x16_bf16 v[80:95], v[154:157], v[184:187], v[80:95]
	s_waitcnt lgkmcnt(2)
	v_mfma_f32_32x32x16_bf16 v[96:111], v[158:161], v[180:183], v[96:111]
	v_mfma_f32_32x32x16_bf16 v[80:95], v[162:165], v[180:183], v[80:95]
	s_waitcnt lgkmcnt(0)
	v_mfma_f32_32x32x16_bf16 v[96:111], v[166:169], v[176:179], v[96:111]
	v_mfma_f32_32x32x16_bf16 v[80:95], v[170:173], v[176:179], v[80:95]
	s_cbranch_scc1 .LBB0_1530
	v_add_u32_e32 v0, s78, v229
	v_subrev_u32_e32 v2, 63, v0
	v_cmp_gt_i32_e32 vcc, v2, v228
	s_nop 6
	v_cndmask_b32_e32 v3, v96, v233, vcc
	v_cmp_lt_i32_e32 vcc, v2, v228
	v_subrev_u32_e32 v2, 61, v0
	s_nop 0
	v_cndmask_b32_e32 v96, v3, v96, vcc
	v_cndmask_b32_e32 v97, v233, v97, vcc
	v_cmp_le_i32_e32 vcc, v2, v228
	v_subrev_u32_e32 v2, 60, v0
	s_nop 0
	v_cndmask_b32_e32 v98, v233, v98, vcc
	v_cmp_le_i32_e32 vcc, v2, v228
	v_subrev_u32_e32 v2, 55, v0
	s_nop 0
	v_cndmask_b32_e32 v99, v233, v99, vcc
	v_cmp_le_i32_e32 vcc, v2, v228
	v_subrev_u32_e32 v2, 54, v0
	s_nop 0
	v_cndmask_b32_e32 v100, v233, v100, vcc
	v_cmp_le_i32_e32 vcc, v2, v228
	v_subrev_u32_e32 v2, 53, v0
	s_nop 0
	v_cndmask_b32_e32 v101, v233, v101, vcc
	v_cmp_le_i32_e32 vcc, v2, v228
	v_subrev_u32_e32 v2, 52, v0
	s_nop 0
	v_cndmask_b32_e32 v102, v233, v102, vcc
	v_cmp_le_i32_e32 vcc, v2, v228
	v_subrev_u32_e32 v2, 47, v0
	s_nop 0
	v_cndmask_b32_e32 v103, v233, v103, vcc
	v_cmp_le_i32_e32 vcc, v2, v228
	v_subrev_u32_e32 v2, 46, v0
	s_nop 0
	v_cndmask_b32_e32 v104, v233, v104, vcc
	v_cmp_le_i32_e32 vcc, v2, v228
	v_subrev_u32_e32 v2, 45, v0
	s_nop 0
	v_cndmask_b32_e32 v105, v233, v105, vcc
	v_cmp_le_i32_e32 vcc, v2, v228
	v_subrev_u32_e32 v2, 44, v0
	s_nop 0
	v_cndmask_b32_e32 v106, v233, v106, vcc
	v_cmp_le_i32_e32 vcc, v2, v228
	v_subrev_u32_e32 v2, 39, v0
	s_nop 0
	v_cndmask_b32_e32 v107, v233, v107, vcc
	v_cmp_le_i32_e32 vcc, v2, v228
	v_subrev_u32_e32 v2, 38, v0
	s_nop 0
	v_cndmask_b32_e32 v108, v233, v108, vcc
	v_cmp_le_i32_e32 vcc, v2, v228
	v_subrev_u32_e32 v2, 37, v0
	s_nop 0
	v_cndmask_b32_e32 v109, v233, v109, vcc
	v_cmp_le_i32_e32 vcc, v2, v228
	v_subrev_u32_e32 v2, 36, v0
	s_nop 0
	v_cndmask_b32_e32 v110, v233, v110, vcc
	v_cmp_le_i32_e32 vcc, v2, v228
	v_subrev_u32_e32 v2, 31, v0
	s_nop 0
	v_cndmask_b32_e32 v111, v233, v111, vcc
	v_cmp_le_i32_e32 vcc, v2, v228
	v_subrev_u32_e32 v2, 30, v0
	s_nop 0
	v_cndmask_b32_e32 v80, v233, v80, vcc
	v_cmp_le_i32_e32 vcc, v2, v228
	v_subrev_u32_e32 v2, 29, v0
	s_nop 0
	v_cndmask_b32_e32 v81, v233, v81, vcc
	v_cmp_le_i32_e32 vcc, v2, v228
	v_subrev_u32_e32 v2, 28, v0
	s_nop 0
	v_cndmask_b32_e32 v82, v233, v82, vcc
	v_cmp_le_i32_e32 vcc, v2, v228
	v_subrev_u32_e32 v2, 23, v0
	s_nop 0
	v_cndmask_b32_e32 v83, v233, v83, vcc
	v_cmp_le_i32_e32 vcc, v2, v228
	v_subrev_u32_e32 v2, 22, v0
	s_nop 0
	v_cndmask_b32_e32 v84, v233, v84, vcc
	v_cmp_le_i32_e32 vcc, v2, v228
	v_subrev_u32_e32 v2, 21, v0
	s_nop 0
	v_cndmask_b32_e32 v85, v233, v85, vcc
	v_cmp_le_i32_e32 vcc, v2, v228
	v_subrev_u32_e32 v2, 20, v0
	s_nop 0
	v_cndmask_b32_e32 v86, v233, v86, vcc
	v_cmp_le_i32_e32 vcc, v2, v228
	v_add_u32_e32 v2, -15, v0
	s_nop 0
	v_cndmask_b32_e32 v87, v233, v87, vcc
	v_cmp_le_i32_e32 vcc, v2, v228
	v_add_u32_e32 v2, -14, v0
	s_nop 0
	v_cndmask_b32_e32 v88, v233, v88, vcc
	v_cmp_le_i32_e32 vcc, v2, v228
	v_add_u32_e32 v2, -13, v0
	s_nop 0
	v_cndmask_b32_e32 v89, v233, v89, vcc
	v_cmp_le_i32_e32 vcc, v2, v228
	v_add_u32_e32 v2, -12, v0
	s_nop 0
	v_cndmask_b32_e32 v90, v233, v90, vcc
	v_cmp_le_i32_e32 vcc, v2, v228
	v_add_u32_e32 v2, -7, v0
	s_nop 0
	v_cndmask_b32_e32 v91, v233, v91, vcc
	v_cmp_le_i32_e32 vcc, v2, v228
	v_add_u32_e32 v2, -6, v0
	s_nop 0
	v_cndmask_b32_e32 v92, v233, v92, vcc
	v_cmp_le_i32_e32 vcc, v2, v228
	v_add_u32_e32 v2, -5, v0
	v_add_u32_e32 v0, -4, v0
	v_cndmask_b32_e32 v93, v233, v93, vcc
	v_cmp_le_i32_e32 vcc, v2, v228
	s_nop 1
	v_cndmask_b32_e32 v94, v233, v94, vcc
	v_cmp_le_i32_e32 vcc, v0, v228
	s_nop 1
	v_cndmask_b32_e32 v95, v233, v95, vcc

; #define LAS __attribute__((address_space(3)))
; __device__ __forceinline__ void attn_phase(LAS unsigned char* ldsb, bf16_t* P, const bf16_t* Kn, const bf16_t* KPE, const bf16_t* VT) {
;     ...
;             ATT_LOAD(0);
;             for (int kt = 0; kt < nt; ++kt) {
;                 __syncthreads();
; #pragma unroll
;                 for (int i = 0; i < 3; ++i) { const int id = tid + 512 * i, row = id / 24, ch = id % 24; *(LAS u32x4*)(sK + row * 200 + ch * 8) = kst[i]; }
; #pragma unroll
;                 for (int i = 0; i < 2; ++i) { const int id = tid + 512 * i, d = id >> 3, ch = id & 7;
;                     *(LAS u32x2*)(sVt + d * 68 + ch * 8) = (u32x2){vst[i].x, vst[i].y}; *(LAS u32x2*)(sVt + d * 68 + ch * 8 + 4) = (u32x2){vst[i].z, vst[i].w}; }
;                 __syncthreads();
;                 if (kt + 1 < nt) ATT_LOAD(kt + 1);
;                 const int k0 = kt * 64;
;                 if (k0 <= q0 + w * 32 + 31) {
;                     f32x16 st[2];
; #pragma unroll
;                     for (int kb = 0; kb < 2; ++kb) for (int i = 0; i < 16; ++i) st[kb][i] = 0.f;
;                     {
;                         const unsigned kaddr = (unsigned)(size_t)(sK + r * 200 + hh * 8);
;                         bf16x8 ka0, ka1, kb0, kb1;
;     ...
;                         ATT_RD(ka0, 0);   ATT_RD(ka1, 12800);
;                         ATT_RD(kb0, 32);  ATT_RD(kb1, 12832);  ATT_WT(2, ka0, ka1); ATT_MM(ka0, ka1, 0);
;                         ATT_RD(ka0, 64);  ATT_RD(ka1, 12864);  ATT_WT(2, kb0, kb1); ATT_MM(kb0, kb1, 1);
;                         ATT_RD(kb0, 96);  ATT_RD(kb1, 12896);  ATT_WT(2, ka0, ka1); ATT_MM(ka0, ka1, 2);
;                         ATT_RD(ka0, 128); ATT_RD(ka1, 12928);  ATT_WT(2, kb0, kb1); ATT_MM(kb0, kb1, 3);
;                         ATT_RD(kb0, 160); ATT_RD(kb1, 12960);  ATT_WT(2, ka0, ka1); ATT_MM(ka0, ka1, 4);
;                         ATT_RD(ka0, 192); ATT_RD(ka1, 12992);  ATT_WT(2, kb0, kb1); ATT_MM(kb0, kb1, 5);
;                         ATT_RD(kb0, 224); ATT_RD(kb1, 13024);  ATT_WT(2, ka0, ka1); ATT_MM(ka0, ka1, 6);
;                         ATT_RD(ka0, 256); ATT_RD(ka1, 13056);  ATT_WT(2, kb0, kb1); ATT_MM(kb0, kb1, 7);
;                         ATT_RD(kb0, 288); ATT_RD(kb1, 13088);  ATT_WT(2, ka0, ka1); ATT_MM(ka0, ka1, 8);
;                         ATT_RD(ka0, 320); ATT_RD(ka1, 13120);  ATT_WT(2, kb0, kb1); ATT_MM(kb0, kb1, 9);
.Lattn_fast_st:
	ds_read_b128 v[154:157], v241 offset:0
	ds_read_b128 v[158:161], v241 offset:32
	ds_read_b128 v[162:165], v241 offset:64
	ds_read_b128 v[166:169], v241 offset:96
	ds_read_b128 v[170:173], v241 offset:128
	ds_read_b128 v[244:247], v241 offset:160
	s_waitcnt lgkmcnt(5)
	v_mfma_f32_32x32x16_bf16 v[96:111], v[154:157], v[220:223], 0
	ds_read_b128 v[248:251], v241 offset:192
	s_waitcnt vmcnt(0)
	ds_write_b128 v148, v[112:115]
	ds_write_b128 v149, v[116:119]
	s_waitcnt lgkmcnt(7)
	v_mfma_f32_32x32x16_bf16 v[96:111], v[158:161], v[216:219], v[96:111]
	ds_read_b128 v[252:255], v241 offset:224
	ds_write_b128 v150, v[120:123]
	s_waitcnt lgkmcnt(8)
	v_mfma_f32_32x32x16_bf16 v[96:111], v[162:165], v[212:215], v[96:111]
	ds_read_b128 v[154:157], v241 offset:256
	ds_write2_b64 v151, v[128:129], v[130:131] offset1:1
	s_waitcnt lgkmcnt(9)
	v_mfma_f32_32x32x16_bf16 v[96:111], v[166:169], v[208:211], v[96:111]
	ds_read_b128 v[158:161], v241 offset:288
	ds_write2_b64 v152, v[124:125], v[126:127] offset1:1
	s_waitcnt lgkmcnt(10)
	v_mfma_f32_32x32x16_bf16 v[96:111], v[170:173], v[204:207], v[96:111]
	ds_read_b128 v[162:165], v241 offset:320
	s_waitcnt lgkmcnt(10)
	v_mfma_f32_32x32x16_bf16 v[96:111], v[244:247], v[200:203], v[96:111]
	ds_read_b128 v[166:169], v241 offset:352
	s_waitcnt lgkmcnt(10)
	v_mfma_f32_32x32x16_bf16 v[96:111], v[248:251], v[196:199], v[96:111]
	ds_read_b128 v[170:173], v241 offset:12800
	s_waitcnt lgkmcnt(8)
	v_mfma_f32_32x32x16_bf16 v[96:111], v[252:255], v[192:195], v[96:111]
	ds_read_b128 v[244:247], v241 offset:12832
	s_waitcnt lgkmcnt(7)
	v_mfma_f32_32x32x16_bf16 v[96:111], v[154:157], v[188:191], v[96:111]
	ds_read_b128 v[248:251], v241 offset:12864
	s_waitcnt lgkmcnt(6)
	v_mfma_f32_32x32x16_bf16 v[96:111], v[158:161], v[184:187], v[96:111]
	ds_read_b128 v[252:255], v241 offset:12896
	s_waitcnt lgkmcnt(5)
	v_mfma_f32_32x32x16_bf16 v[96:111], v[162:165], v[180:183], v[96:111]
	ds_read_b128 v[154:157], v241 offset:12928
	global_load_dwordx4 v[112:115], v136, s[26:27]
	global_load_dwordx4 v[116:119], v140, s[26:27]
	global_load_dwordx4 v[120:123], v144, s[26:27]
	global_load_dwordx4 v[128:131], v132, s[26:27]
	global_load_dwordx4 v[124:127], v134, s[26:27]
	s_waitcnt lgkmcnt(5)
	v_mfma_f32_32x32x16_bf16 v[96:111], v[166:169], v[176:179], v[96:111]
	ds_read_b128 v[158:161], v241 offset:12960
	v_add_u32_e32 v132, 0x80, v132
	v_add_u32_e32 v134, 0x80, v134
	v_add_u32_e32 v136, v136, v138
	v_add_u32_e32 v140, v140, v142
	v_add_u32_e32 v144, v144, v146
	s_waitcnt lgkmcnt(5)
	v_mfma_f32_32x32x16_bf16 v[80:95], v[170:173], v[220:223], 0
	ds_read_b128 v[162:165], v241 offset:12992
	s_waitcnt lgkmcnt(5)
	v_mfma_f32_32x32x16_bf16 v[80:95], v[244:247], v[216:219], v[80:95]
	ds_read_b128 v[166:169], v241 offset:13024
	s_waitcnt lgkmcnt(5)
	v_mfma_f32_32x32x16_bf16 v[80:95], v[248:251], v[212:215], v[80:95]
	ds_read_b128 v[170:173], v241 offset:13056
	s_waitcnt lgkmcnt(5)
	v_mfma_f32_32x32x16_bf16 v[80:95], v[252:255], v[208:211], v[80:95]
	ds_read_b128 v[244:247], v241 offset:13088
	s_waitcnt lgkmcnt(5)
	v_mfma_f32_32x32x16_bf16 v[80:95], v[154:157], v[204:207], v[80:95]
	ds_read_b128 v[248:251], v241 offset:13120
	v_max_f32_e32 v14, v97, v97
	v_max_f32_e32 v15, v96, v96
	v_max_f32_e32 v14, v15, v14
	v_max3_f32 v14, v14, v98, v99
	v_max3_f32 v14, v14, v100, v101
	v_max3_f32 v14, v14, v102, v103
	v_max3_f32 v14, v14, v104, v105
	s_waitcnt lgkmcnt(5)
	v_mfma_f32_32x32x16_bf16 v[80:95], v[158:161], v[200:203], v[80:95]
	ds_read_b128 v[252:255], v241 offset:13152
	v_max3_f32 v14, v14, v106, v107
	v_max3_f32 v14, v14, v108, v109
	v_max3_f32 v14, v14, v110, v111
	v_sub_f32_e32 v15, v14, v240
	v_cmp_lt_f32_e32 vcc, 4.0, v15
	s_cbranch_vccnz .Lf_rare0_st
